# L0 in-projection epilogue: the eight row-scale loads issued together at the block top (each was behind a vmcnt(0) that also drained the previous stores)
# speedup vs baseline: 1.1420x; 1.0034x over previous
; DI unsigned pk2(float lo, float hi) { f32x2 v = {lo, hi}; bf16x2_t b = __builtin_convertvector(v, bf16x2_t); return __builtin_bit_cast(unsigned, b); }
; DI float rs_from_ss(u64 ssq) { return rsqrtf((float)ssq * (1.f / (1048576.f * 1024.f)) + EPS); }
;     DI void operator()(const AccT& acc, const Unit& u, int wr, int wc, int fr, int fq) const {
;         const int row0 = u.pm * 256 + wr * 64 + fr, col0 = u.pn * 256 + wc * 32 + 8 * fq;
; #pragma unroll
;         for (int ai = 0; ai < 2; ++ai)
; #pragma unroll
;             for (int m = 0; m < 4; ++m) { const int row = row0 + ai * 128 + m * 16;
;                 float s = 1.f; if (SMODE == 1) s = rs_from_ss(((const u64*)sc)[row]); if (SMODE == 2) s = ((const float*)sc)[row];
;                 bf16_t* rowp = O + (size_t)row * ldc + col0;
; #pragma unroll
;                 for (int bj = 0; bj < 2; ++bj) { const f32x4 v0 = acc[ai][bj][m][0] * s, v1 = acc[ai][bj][m][1] * s;
;                     u32x4 w; w.x = pk2(v0[0], v0[1]); w.y = pk2(v0[2], v0[3]); w.z = pk2(v1[0], v1[1]); w.w = pk2(v1[2], v1[3]);
;                     *(u32x4*)(rowp + bj * 128) = w; } }
.LBB0_384:
	v_lshl_add_u32 v144, s6, 8, v158
	v_ashrrev_i32_e32 v145, 31, v144
	v_lshl_add_u64 v[150:151], v[144:145], 3, s[8:9]
	global_load_dwordx2 v[200:201], v[150:151], off
	global_load_dwordx2 v[202:203], v[150:151], off offset:128
	global_load_dwordx2 v[204:205], v[150:151], off offset:256
	global_load_dwordx2 v[206:207], v[150:151], off offset:384
	global_load_dwordx2 v[208:209], v[150:151], off offset:1024
	global_load_dwordx2 v[210:211], v[150:151], off offset:1152
	global_load_dwordx2 v[212:213], v[150:151], off offset:1280
	global_load_dwordx2 v[214:215], v[150:151], off offset:1408
	s_nop 1
	v_lshl_or_b32 v166, s7, 8, v160
	v_mov_b64_e32 v[146:147], s[2:3]
	v_ashrrev_i32_e32 v167, 31, v166
	v_mad_i64_i32 v[168:169], s[6:7], v144, s55, v[146:147]
	v_or_b32_e32 v170, 16, v144
	v_ashrrev_i32_e32 v171, 31, v170
	s_waitcnt vmcnt(7)
	v_ffbh_u32_e32 v145, v201
	v_min_u32_e32 v145, 32, v145
	v_lshlrev_b64 v[148:149], v145, v[200:201]
	v_min_u32_e32 v148, 1, v148
	v_or_b32_e32 v148, v149, v148
	v_cvt_f32_u32_e32 v165, v148
	v_sub_u32_e32 v145, 32, v145
	v_lshlrev_b64 v[148:149], 1, v[166:167]
	v_lshl_add_u64 v[166:167], v[168:169], 0, v[148:149]
	v_ldexp_f32 v145, v165, v145
	v_fmamk_f32 v145, v145, 0x30800000, v164
	v_mul_f32_e32 v165, 0x4b800000, v145
	v_cmp_gt_f32_e32 vcc, s54, v145
	v_lshl_add_u64 v[168:169], v[170:171], 3, s[8:9]
	s_nop 0
	v_cndmask_b32_e32 v145, v145, v165, vcc
	v_rsq_f32_e32 v145, v145
	s_nop 0
	v_mul_f32_e32 v165, 0x45800000, v145
	v_cndmask_b32_e32 v172, v145, v165, vcc
	v_pk_mul_f32 v[122:123], v[122:123], v[172:173] op_sel_hi:[1,0]
	v_pk_mul_f32 v[120:121], v[120:121], v[172:173] op_sel_hi:[1,0]
	v_pk_mul_f32 v[126:127], v[126:127], v[172:173] op_sel_hi:[1,0]
	v_pk_mul_f32 v[124:125], v[124:125], v[172:173] op_sel_hi:[1,0]
	v_pk_mul_f32 v[118:119], v[118:119], v[172:173] op_sel_hi:[1,0]
	v_pk_mul_f32 v[116:117], v[116:117], v[172:173] op_sel_hi:[1,0]
	v_pk_mul_f32 v[174:175], v[114:115], v[172:173] op_sel_hi:[1,0]
	v_pk_mul_f32 v[172:173], v[112:113], v[172:173] op_sel_hi:[1,0]
	v_cvt_pk_bf16_f32 v112, v120, v121
	v_cvt_pk_bf16_f32 v113, v122, v123
	v_cvt_pk_bf16_f32 v114, v124, v125
	v_cvt_pk_bf16_f32 v115, v126, v127
	v_cvt_pk_bf16_f32 v116, v116, v117
	v_cvt_pk_bf16_f32 v117, v118, v119
	v_cvt_pk_bf16_f32 v118, v172, v173
	v_cvt_pk_bf16_f32 v119, v174, v175
	global_store_dwordx4 v[166:167], v[112:115], off
	global_store_dwordx4 v[166:167], v[116:119], off offset:256
	s_nop 1
	v_or_b32_e32 v114, 32, v144
	s_waitcnt vmcnt(8)
	v_ffbh_u32_e32 v115, v203
	v_min_u32_e32 v115, 32, v115
	v_lshlrev_b64 v[112:113], v115, v[202:203]
	v_min_u32_e32 v112, 1, v112
	v_or_b32_e32 v112, v113, v112
	v_cvt_f32_u32_e32 v116, v112
	v_sub_u32_e32 v115, 32, v115
	v_mad_i64_i32 v[112:113], s[6:7], v170, s55, v[146:147]
	v_ldexp_f32 v115, v116, v115
	v_fmamk_f32 v115, v115, 0x30800000, v164
	v_mul_f32_e32 v116, 0x4b800000, v115
	v_cmp_gt_f32_e32 vcc, s54, v115
	v_lshl_add_u64 v[112:113], v[112:113], 0, v[148:149]
	s_nop 0
	v_cndmask_b32_e32 v115, v115, v116, vcc
	v_rsq_f32_e32 v118, v115
	v_ashrrev_i32_e32 v115, 31, v114
	v_lshl_add_u64 v[116:117], v[114:115], 3, s[8:9]
	v_mul_f32_e32 v115, 0x45800000, v118
	v_cndmask_b32_e32 v118, v118, v115, vcc
	v_pk_mul_f32 v[110:111], v[110:111], v[118:119] op_sel_hi:[1,0]
	v_pk_mul_f32 v[108:109], v[108:109], v[118:119] op_sel_hi:[1,0]
	v_pk_mul_f32 v[106:107], v[106:107], v[118:119] op_sel_hi:[1,0]
	v_pk_mul_f32 v[104:105], v[104:105], v[118:119] op_sel_hi:[1,0]
	v_pk_mul_f32 v[102:103], v[102:103], v[118:119] op_sel_hi:[1,0]
	v_pk_mul_f32 v[100:101], v[100:101], v[118:119] op_sel_hi:[1,0]
	v_pk_mul_f32 v[120:121], v[98:99], v[118:119] op_sel_hi:[1,0]
	v_pk_mul_f32 v[118:119], v[96:97], v[118:119] op_sel_hi:[1,0]
	v_cvt_pk_bf16_f32 v96, v108, v109
	v_cvt_pk_bf16_f32 v97, v110, v111
	v_cvt_pk_bf16_f32 v98, v104, v105
	v_cvt_pk_bf16_f32 v99, v106, v107
	v_cvt_pk_bf16_f32 v100, v100, v101
	v_cvt_pk_bf16_f32 v101, v102, v103
	v_cvt_pk_bf16_f32 v102, v118, v119
	v_cvt_pk_bf16_f32 v103, v120, v121
	global_store_dwordx4 v[112:113], v[96:99], off
	global_store_dwordx4 v[112:113], v[100:103], off offset:256
	s_nop 1
	v_or_b32_e32 v98, 48, v144
	s_waitcnt vmcnt(9)
	v_ffbh_u32_e32 v99, v205
	v_min_u32_e32 v99, 32, v99
	v_lshlrev_b64 v[96:97], v99, v[204:205]
	v_min_u32_e32 v96, 1, v96
	v_or_b32_e32 v96, v97, v96
	v_cvt_f32_u32_e32 v100, v96
	v_sub_u32_e32 v99, 32, v99
	v_mad_i64_i32 v[96:97], s[6:7], v114, s55, v[146:147]
	v_ldexp_f32 v99, v100, v99
	v_fmamk_f32 v99, v99, 0x30800000, v164
	v_mul_f32_e32 v100, 0x4b800000, v99
	v_cmp_gt_f32_e32 vcc, s54, v99
	v_lshl_add_u64 v[96:97], v[96:97], 0, v[148:149]
	s_nop 0
	v_cndmask_b32_e32 v99, v99, v100, vcc
	v_rsq_f32_e32 v102, v99
	v_ashrrev_i32_e32 v99, 31, v98
	v_lshl_add_u64 v[100:101], v[98:99], 3, s[8:9]
	v_mul_f32_e32 v99, 0x45800000, v102
	v_cndmask_b32_e32 v102, v102, v99, vcc
	v_pk_mul_f32 v[94:95], v[94:95], v[102:103] op_sel_hi:[1,0]
	v_pk_mul_f32 v[92:93], v[92:93], v[102:103] op_sel_hi:[1,0]
	v_pk_mul_f32 v[90:91], v[90:91], v[102:103] op_sel_hi:[1,0]
	v_pk_mul_f32 v[88:89], v[88:89], v[102:103] op_sel_hi:[1,0]
	v_pk_mul_f32 v[86:87], v[86:87], v[102:103] op_sel_hi:[1,0]
	v_pk_mul_f32 v[84:85], v[84:85], v[102:103] op_sel_hi:[1,0]
	v_pk_mul_f32 v[104:105], v[82:83], v[102:103] op_sel_hi:[1,0]
	v_pk_mul_f32 v[102:103], v[80:81], v[102:103] op_sel_hi:[1,0]
	v_cvt_pk_bf16_f32 v80, v92, v93
	v_cvt_pk_bf16_f32 v81, v94, v95
	v_cvt_pk_bf16_f32 v82, v88, v89
	v_cvt_pk_bf16_f32 v83, v90, v91
	v_cvt_pk_bf16_f32 v84, v84, v85
	v_cvt_pk_bf16_f32 v85, v86, v87
	v_cvt_pk_bf16_f32 v86, v102, v103
	v_cvt_pk_bf16_f32 v87, v104, v105
	global_store_dwordx4 v[96:97], v[80:83], off
	global_store_dwordx4 v[96:97], v[84:87], off offset:256
	s_nop 1
	s_waitcnt vmcnt(10)
; DI unsigned pk2(float lo, float hi) { f32x2 v = {lo, hi}; bf16x2_t b = __builtin_convertvector(v, bf16x2_t); return __builtin_bit_cast(unsigned, b); }
; DI float rs_from_ss(u64 ssq) { return rsqrtf((float)ssq * (1.f / (1048576.f * 1024.f)) + EPS); }
;     DI void operator()(const AccT& acc, const Unit& u, int wr, int wc, int fr, int fq) const {
;         const int row0 = u.pm * 256 + wr * 64 + fr, col0 = u.pn * 256 + wc * 32 + 8 * fq;
; #pragma unroll
;         for (int ai = 0; ai < 2; ++ai)
; #pragma unroll
;             for (int m = 0; m < 4; ++m) { const int row = row0 + ai * 128 + m * 16;
;                 float s = 1.f; if (SMODE == 1) s = rs_from_ss(((const u64*)sc)[row]); if (SMODE == 2) s = ((const float*)sc)[row];
;                 bf16_t* rowp = O + (size_t)row * ldc + col0;
; #pragma unroll
;                 for (int bj = 0; bj < 2; ++bj) { const f32x4 v0 = acc[ai][bj][m][0] * s, v1 = acc[ai][bj][m][1] * s;
;                     u32x4 w; w.x = pk2(v0[0], v0[1]); w.y = pk2(v0[2], v0[3]); w.z = pk2(v1[0], v1[1]); w.w = pk2(v1[2], v1[3]);
;                     *(u32x4*)(rowp + bj * 128) = w; } }
	v_ffbh_u32_e32 v82, v207
	v_min_u32_e32 v82, 32, v82
	v_lshlrev_b64 v[80:81], v82, v[206:207]
	v_min_u32_e32 v80, 1, v80
	v_or_b32_e32 v80, v81, v80
	v_cvt_f32_u32_e32 v80, v80
	v_sub_u32_e32 v81, 32, v82
	v_ldexp_f32 v80, v80, v81
	v_fmamk_f32 v80, v80, 0x30800000, v164
	v_mul_f32_e32 v81, 0x4b800000, v80
	v_cmp_gt_f32_e32 vcc, s54, v80
	s_nop 1
	v_cndmask_b32_e32 v80, v80, v81, vcc
	v_rsq_f32_e32 v82, v80
	v_mad_i64_i32 v[80:81], s[6:7], v98, s55, v[146:147]
	v_lshl_add_u64 v[80:81], v[80:81], 0, v[148:149]
	v_mul_f32_e32 v83, 0x45800000, v82
	v_cndmask_b32_e32 v82, v82, v83, vcc
	v_pk_mul_f32 v[78:79], v[78:79], v[82:83] op_sel_hi:[1,0]
	v_pk_mul_f32 v[76:77], v[76:77], v[82:83] op_sel_hi:[1,0]
	v_pk_mul_f32 v[74:75], v[74:75], v[82:83] op_sel_hi:[1,0]
	v_pk_mul_f32 v[72:73], v[72:73], v[82:83] op_sel_hi:[1,0]
	v_pk_mul_f32 v[70:71], v[70:71], v[82:83] op_sel_hi:[1,0]
	v_pk_mul_f32 v[68:69], v[68:69], v[82:83] op_sel_hi:[1,0]
	v_pk_mul_f32 v[84:85], v[66:67], v[82:83] op_sel_hi:[1,0]
	v_pk_mul_f32 v[82:83], v[64:65], v[82:83] op_sel_hi:[1,0]
	v_cvt_pk_bf16_f32 v64, v76, v77
	v_cvt_pk_bf16_f32 v65, v78, v79
	v_cvt_pk_bf16_f32 v66, v72, v73
	v_cvt_pk_bf16_f32 v67, v74, v75
	v_cvt_pk_bf16_f32 v68, v68, v69
	v_cvt_pk_bf16_f32 v69, v70, v71
	v_cvt_pk_bf16_f32 v70, v82, v83
	v_cvt_pk_bf16_f32 v71, v84, v85
	global_store_dwordx4 v[80:81], v[64:67], off
	global_store_dwordx4 v[80:81], v[68:71], off offset:256
	s_nop 1
	s_waitcnt vmcnt(11)
	v_ffbh_u32_e32 v66, v209
	v_min_u32_e32 v66, 32, v66
	v_lshlrev_b64 v[64:65], v66, v[208:209]
	v_min_u32_e32 v64, 1, v64
	v_or_b32_e32 v64, v65, v64
	v_cvt_f32_u32_e32 v64, v64
	v_sub_u32_e32 v66, 32, v66
	v_add_u32_e32 v65, 0x80, v144
	v_ldexp_f32 v64, v64, v66
	v_fmamk_f32 v64, v64, 0x30800000, v164
	v_mul_f32_e32 v66, 0x4b800000, v64
	v_cmp_gt_f32_e32 vcc, s54, v64
	s_nop 1
	v_cndmask_b32_e32 v64, v64, v66, vcc
	v_rsq_f32_e32 v66, v64
	v_mad_i64_i32 v[64:65], s[6:7], v65, s55, v[146:147]
	v_lshl_add_u64 v[64:65], v[64:65], 0, v[148:149]
	v_mul_f32_e32 v67, 0x45800000, v66
	v_cndmask_b32_e32 v66, v66, v67, vcc
	v_pk_mul_f32 v[62:63], v[62:63], v[66:67] op_sel_hi:[1,0]
	v_pk_mul_f32 v[60:61], v[60:61], v[66:67] op_sel_hi:[1,0]
	v_pk_mul_f32 v[58:59], v[58:59], v[66:67] op_sel_hi:[1,0]
	v_pk_mul_f32 v[56:57], v[56:57], v[66:67] op_sel_hi:[1,0]
	v_pk_mul_f32 v[54:55], v[54:55], v[66:67] op_sel_hi:[1,0]
	v_pk_mul_f32 v[52:53], v[52:53], v[66:67] op_sel_hi:[1,0]
	v_pk_mul_f32 v[68:69], v[50:51], v[66:67] op_sel_hi:[1,0]
	v_pk_mul_f32 v[66:67], v[48:49], v[66:67] op_sel_hi:[1,0]
	v_cvt_pk_bf16_f32 v48, v60, v61
	v_cvt_pk_bf16_f32 v49, v62, v63
	v_cvt_pk_bf16_f32 v50, v56, v57
	v_cvt_pk_bf16_f32 v51, v58, v59
	v_cvt_pk_bf16_f32 v52, v52, v53
	v_cvt_pk_bf16_f32 v53, v54, v55
	v_cvt_pk_bf16_f32 v54, v66, v67
	v_cvt_pk_bf16_f32 v55, v68, v69
	global_store_dwordx4 v[64:65], v[48:51], off
	global_store_dwordx4 v[64:65], v[52:55], off offset:256
	s_nop 1
	s_waitcnt vmcnt(12)
	v_ffbh_u32_e32 v50, v211
	v_min_u32_e32 v50, 32, v50
	v_lshlrev_b64 v[48:49], v50, v[210:211]
	v_min_u32_e32 v48, 1, v48
	v_or_b32_e32 v48, v49, v48
	v_cvt_f32_u32_e32 v48, v48
	v_sub_u32_e32 v50, 32, v50
	v_add_u32_e32 v49, 0x90, v144
	v_ldexp_f32 v48, v48, v50
	v_fmamk_f32 v48, v48, 0x30800000, v164
	v_mul_f32_e32 v50, 0x4b800000, v48
	v_cmp_gt_f32_e32 vcc, s54, v48
	s_nop 1
	v_cndmask_b32_e32 v48, v48, v50, vcc
	v_rsq_f32_e32 v50, v48
	v_mad_i64_i32 v[48:49], s[6:7], v49, s55, v[146:147]
	v_lshl_add_u64 v[48:49], v[48:49], 0, v[148:149]
	v_mul_f32_e32 v51, 0x45800000, v50
	v_cndmask_b32_e32 v50, v50, v51, vcc
	v_pk_mul_f32 v[46:47], v[46:47], v[50:51] op_sel_hi:[1,0]
	v_pk_mul_f32 v[44:45], v[44:45], v[50:51] op_sel_hi:[1,0]
	v_pk_mul_f32 v[42:43], v[42:43], v[50:51] op_sel_hi:[1,0]
	v_pk_mul_f32 v[40:41], v[40:41], v[50:51] op_sel_hi:[1,0]
	v_pk_mul_f32 v[38:39], v[38:39], v[50:51] op_sel_hi:[1,0]
	v_pk_mul_f32 v[36:37], v[36:37], v[50:51] op_sel_hi:[1,0]
	v_pk_mul_f32 v[52:53], v[34:35], v[50:51] op_sel_hi:[1,0]
	v_pk_mul_f32 v[50:51], v[32:33], v[50:51] op_sel_hi:[1,0]
	v_cvt_pk_bf16_f32 v32, v44, v45
	v_cvt_pk_bf16_f32 v33, v46, v47
	v_cvt_pk_bf16_f32 v34, v40, v41
	v_cvt_pk_bf16_f32 v35, v42, v43
	v_cvt_pk_bf16_f32 v36, v36, v37
	v_cvt_pk_bf16_f32 v37, v38, v39
	v_cvt_pk_bf16_f32 v38, v50, v51
	v_cvt_pk_bf16_f32 v39, v52, v53
	global_store_dwordx4 v[48:49], v[32:35], off
	global_store_dwordx4 v[48:49], v[36:39], off offset:256
	s_nop 1
	s_waitcnt vmcnt(13)
; DI unsigned pk2(float lo, float hi) { f32x2 v = {lo, hi}; bf16x2_t b = __builtin_convertvector(v, bf16x2_t); return __builtin_bit_cast(unsigned, b); }
; DI float rs_from_ss(u64 ssq) { return rsqrtf((float)ssq * (1.f / (1048576.f * 1024.f)) + EPS); }
;     DI void operator()(const AccT& acc, const Unit& u, int wr, int wc, int fr, int fq) const {
;         const int row0 = u.pm * 256 + wr * 64 + fr, col0 = u.pn * 256 + wc * 32 + 8 * fq;
; #pragma unroll
;         for (int ai = 0; ai < 2; ++ai)
; #pragma unroll
;             for (int m = 0; m < 4; ++m) { const int row = row0 + ai * 128 + m * 16;
;                 float s = 1.f; if (SMODE == 1) s = rs_from_ss(((const u64*)sc)[row]); if (SMODE == 2) s = ((const float*)sc)[row];
;                 bf16_t* rowp = O + (size_t)row * ldc + col0;
; #pragma unroll
;                 for (int bj = 0; bj < 2; ++bj) { const f32x4 v0 = acc[ai][bj][m][0] * s, v1 = acc[ai][bj][m][1] * s;
;                     u32x4 w; w.x = pk2(v0[0], v0[1]); w.y = pk2(v0[2], v0[3]); w.z = pk2(v1[0], v1[1]); w.w = pk2(v1[2], v1[3]);
;                     *(u32x4*)(rowp + bj * 128) = w; } }
	v_ffbh_u32_e32 v34, v213
	v_min_u32_e32 v34, 32, v34
	v_lshlrev_b64 v[32:33], v34, v[212:213]
	v_min_u32_e32 v32, 1, v32
	v_or_b32_e32 v32, v33, v32
	v_cvt_f32_u32_e32 v32, v32
	v_sub_u32_e32 v34, 32, v34
	v_add_u32_e32 v33, 0xa0, v144
	v_ldexp_f32 v32, v32, v34
	v_fmamk_f32 v32, v32, 0x30800000, v164
	v_mul_f32_e32 v34, 0x4b800000, v32
	v_cmp_gt_f32_e32 vcc, s54, v32
	s_nop 1
	v_cndmask_b32_e32 v32, v32, v34, vcc
	v_rsq_f32_e32 v34, v32
	v_mad_i64_i32 v[32:33], s[6:7], v33, s55, v[146:147]
	v_lshl_add_u64 v[32:33], v[32:33], 0, v[148:149]
	v_mul_f32_e32 v35, 0x45800000, v34
	v_cndmask_b32_e32 v34, v34, v35, vcc
	v_pk_mul_f32 v[30:31], v[30:31], v[34:35] op_sel_hi:[1,0]
	v_pk_mul_f32 v[28:29], v[28:29], v[34:35] op_sel_hi:[1,0]
	v_pk_mul_f32 v[26:27], v[26:27], v[34:35] op_sel_hi:[1,0]
	v_pk_mul_f32 v[24:25], v[24:25], v[34:35] op_sel_hi:[1,0]
	v_pk_mul_f32 v[22:23], v[22:23], v[34:35] op_sel_hi:[1,0]
	v_pk_mul_f32 v[20:21], v[20:21], v[34:35] op_sel_hi:[1,0]
	v_pk_mul_f32 v[36:37], v[18:19], v[34:35] op_sel_hi:[1,0]
	v_pk_mul_f32 v[34:35], v[16:17], v[34:35] op_sel_hi:[1,0]
	v_cvt_pk_bf16_f32 v16, v28, v29
	v_cvt_pk_bf16_f32 v17, v30, v31
	v_cvt_pk_bf16_f32 v18, v24, v25
	v_cvt_pk_bf16_f32 v19, v26, v27
	v_cvt_pk_bf16_f32 v20, v20, v21
	v_cvt_pk_bf16_f32 v21, v22, v23
	v_cvt_pk_bf16_f32 v22, v34, v35
	v_cvt_pk_bf16_f32 v23, v36, v37
	global_store_dwordx4 v[32:33], v[16:19], off
	global_store_dwordx4 v[32:33], v[20:23], off offset:256
	s_nop 1
	s_andn2_b64 vcc, exec, s[4:5]
	s_mov_b64 s[4:5], -1
	s_waitcnt vmcnt(14)
	v_ffbh_u32_e32 v18, v215
	v_min_u32_e32 v18, 32, v18
	v_lshlrev_b64 v[16:17], v18, v[214:215]
	v_min_u32_e32 v16, 1, v16
	v_or_b32_e32 v16, v17, v16
	v_cvt_f32_u32_e32 v16, v16
	v_sub_u32_e32 v18, 32, v18
	v_add_u32_e32 v17, 0xb0, v144
	v_ldexp_f32 v16, v16, v18
	v_fmamk_f32 v16, v16, 0x30800000, v164
	v_mul_f32_e32 v18, 0x4b800000, v16
	v_cmp_gt_f32_e64 s[6:7], s54, v16
	s_nop 1
	v_cndmask_b32_e64 v16, v16, v18, s[6:7]
	v_rsq_f32_e32 v18, v16
	v_mad_i64_i32 v[16:17], s[24:25], v17, s55, v[146:147]
	v_lshl_add_u64 v[16:17], v[16:17], 0, v[148:149]
	v_mul_f32_e32 v19, 0x45800000, v18
	v_cndmask_b32_e64 v18, v18, v19, s[6:7]
	v_pk_mul_f32 v[14:15], v[14:15], v[18:19] op_sel_hi:[1,0]
	v_pk_mul_f32 v[12:13], v[12:13], v[18:19] op_sel_hi:[1,0]
	v_pk_mul_f32 v[10:11], v[10:11], v[18:19] op_sel_hi:[1,0]
	v_pk_mul_f32 v[8:9], v[8:9], v[18:19] op_sel_hi:[1,0]
	v_pk_mul_f32 v[6:7], v[6:7], v[18:19] op_sel_hi:[1,0]
	v_pk_mul_f32 v[4:5], v[4:5], v[18:19] op_sel_hi:[1,0]
	v_pk_mul_f32 v[20:21], v[2:3], v[18:19] op_sel_hi:[1,0]
	v_pk_mul_f32 v[18:19], v[0:1], v[18:19] op_sel_hi:[1,0]
	v_cvt_pk_bf16_f32 v0, v12, v13
	v_cvt_pk_bf16_f32 v1, v14, v15
	v_cvt_pk_bf16_f32 v2, v8, v9
	v_cvt_pk_bf16_f32 v3, v10, v11
	v_cvt_pk_bf16_f32 v4, v4, v5
	v_cvt_pk_bf16_f32 v5, v6, v7
	v_cvt_pk_bf16_f32 v6, v18, v19
	v_cvt_pk_bf16_f32 v7, v20, v21
	global_store_dwordx4 v[16:17], v[0:3], off
	global_store_dwordx4 v[16:17], v[4:7], off offset:256
	s_cbranch_vccnz .LBB0_376
	s_andn2_b64 vcc, exec, s[0:1]
	s_cbranch_vccnz .LBB0_375
	s_barrier
	s_branch .LBB0_375
